# e27: e25 + P0 rebalance: GEMV workgroups 0..63 run the raw-copy transpose item of transpose workgroup b2 before their GEMV; transpose workgroups (P0's long ones) do 4 items instead of 5
# baseline (speedup 1.0000x reference)
; #define LAS __attribute__((address_space(3)))
; #define SUB(i, ...) do { if (PROBE_PH == phk && PROBE_SUB == (i)) { __syncthreads(); tp0 = __builtin_amdgcn_s_memrealtime(); } __VA_ARGS__ if (PROBE_PH == phk && PROBE_SUB == (i)) { asm volatile("s_waitcnt vmcnt(0)" ::: "memory"); __syncthreads(); tp1 = __builtin_amdgcn_s_memrealtime(); } } while (0)
; __global__ void __launch_bounds__(NTHREADS, 2) mk_fwd(Args a) {
;     ...
;         SUB(0, if (bx < 192) gemv_item((LAS float*)lds, bx, a.in[1], a.in[3], a.in[4], a.in[5], (float*)(a.ws + WS_MOD));
;                else { const int b2 = bx - 192;
;                    transpose_dispatch((16 + b2) * 8 + wave, a.in[7], a.in[20], a.in[18], a.in[8], a.ws, scr, lane);
;                    if (b2 < 16) transpose_dispatch(b2 * 8 + wave, a.in[7], a.in[20], a.in[18], a.in[8], a.ws, scr, lane);
;                    for (int it = 80 + 3 * b2; it < 80 + 3 * b2 + 3; ++it) transpose_dispatch(it * 8 + wave, a.in[7], a.in[20], a.in[18], a.in[8], a.ws, scr, lane);
;                    if (b2 >= 16) transpose_dispatch((272 + b2 - 16) * 8 + wave, a.in[7], a.in[20], a.in[18], a.in[8], a.ws, scr, lane); } );
.LBB0_7:
	s_or_b64 exec, exec, s[2:3]
	s_lshr_b32 s53, s6, 6
	s_cmp_lt_i32 s78, 1
	s_cselect_b64 s[0:1], -1, 0
	s_cmp_gt_i32 s79, 0
	s_cselect_b64 s[2:3], -1, 0
	s_and_b64 s[2:3], s[0:1], s[2:3]
	s_andn2_b64 vcc, exec, s[2:3]
	v_and_b32_e32 v212, 63, v0
	s_cbranch_vccnz .LBB0_78
	s_cmpk_gt_i32 s16, 0xbf
	s_mov_b64 s[4:5], -1
	s_cbranch_scc1 .Lp0_tr
	s_cmp_gt_u32 s16, 63
	s_cbranch_scc1 .LBB0_70
	s_add_i32 s16, s16, 0xc0
	s_mov_b32 s98, 1
	s_branch .Lp0_site1
.Lp0_tr:
	s_mov_b32 s98, 0
	s_mul_i32 s0, s53, 0x2100
	s_add_i32 s1, s0, 0
	s_lshl_b32 s0, s16, 3
	s_add_i32 s0, s0, s53
	s_branch .LBB0_11
.Lp0_site1:
	s_mul_i32 s0, s53, 0x2100
	s_add_i32 s1, s0, 0
	s_lshl_b32 s0, s16, 3
	s_add_i32 s0, s0, s53
	s_add_i32 s8, s0, 0xfffffa80
	s_cmpk_gt_i32 s8, 0x7f
	s_cbranch_scc1 .LBB0_12
	s_andn2_b64 vcc, exec, s[4:5]
	s_cbranch_vccz .LBB0_25
.LBB0_11:
	s_cmp_eq_u32 s98, 1
	s_cbranch_scc1 .Lp0_ret
	s_add_i32 s8, s16, 0xffffff40
	s_cmpk_gt_u32 s16, 0xcf
	s_cbranch_scc0 .LBB0_26
	s_branch .LBB0_42

; #define LAS __attribute__((address_space(3)))
; __device__ __forceinline__ f32x4 ld_nt(const float* p) { return __builtin_nontemporal_load((const f32x4*)p); }
; __device__ __forceinline__ void transpose_item(const float* W, int K, int pitch, int ncols, f16* WT, LAS float* scr, int item, int lane) {
;     const int nblk = ncols / 32, kb = item / nblk, nb = item % nblk, k0 = 64 * kb, n0 = 32 * nb;
;     const int kr = lane >> 3, nq = (lane & 7) * 4;
;     f32x4 v[8];
; #pragma unroll
;     for (int i = 0; i < 8; ++i) v[i] = ld_nt(W + (size_t)(k0 + kr + 8 * i) * pitch + n0 + nq);
;     __builtin_amdgcn_sched_barrier(0);
; #pragma unroll
;     for (int i = 0; i < 8; ++i) { LAS float* sp = scr + (kr + 8 * i) * 33 + nq; sp[0] = v[i][0]; sp[1] = v[i][1]; sp[2] = v[i][2]; sp[3] = v[i][3]; }
;     asm volatile("s_waitcnt lgkmcnt(0)" ::: "memory");
;     const int c = lane & 7;
; #pragma unroll
;     for (int j = 0; j < 4; ++j) { const int n = (lane >> 3) + 8 * j; const LAS float* sp = scr + (8 * c) * 33 + n;
;         u32x4 o; o.x = pk_f16(sp[0 * 33], sp[1 * 33]); o.y = pk_f16(sp[2 * 33], sp[3 * 33]); o.z = pk_f16(sp[4 * 33], sp[5 * 33]); o.w = pk_f16(sp[6 * 33], sp[7 * 33]);
;         *(u32x4*)(WT + (size_t)(n0 + n) * K + k0 + 8 * c) = o; }
;     asm volatile("s_waitcnt lgkmcnt(0)" ::: "memory");
; }
; __global__ void __launch_bounds__(NTHREADS, 2) mk_fwd(Args a) {
;     ...
;                    transpose_dispatch((16 + b2) * 8 + wave, a.in[7], a.in[20], a.in[18], a.in[8], a.ws, scr, lane);
;                    if (b2 < 16) transpose_dispatch(b2 * 8 + wave, a.in[7], a.in[20], a.in[18], a.in[8], a.ws, scr, lane);
;                    for (int it = 80 + 3 * b2; it < 80 + 3 * b2 + 3; ++it) transpose_dispatch(it * 8 + wave, a.in[7], a.in[20], a.in[18], a.in[8], a.ws, scr, lane);
;                    if (b2 >= 16) transpose_dispatch((272 + b2 - 16) * 8 + wave, a.in[7], a.in[20], a.in[18], a.in[8], a.ws, scr, lane); } );
.LBB0_25:
	s_ashr_i32 s4, s8, 31
	s_lshr_b32 s4, s4, 27
	s_add_i32 s9, s8, s4
	s_lshl_b32 s4, s9, 11
	s_and_b32 s4, s4, 0xffff0000
	s_ashr_i32 s5, s4, 31
	s_lshl_b64 s[6:7], s[4:5], 2
	v_readlane_b32 s56, v254, 18
	v_readlane_b32 s57, v254, 19
	s_add_u32 s10, s56, s6
	s_addc_u32 s7, s57, s7
	s_lshl_b64 s[4:5], s[4:5], 1
	s_add_u32 s11, s50, s4
	s_addc_u32 s12, s51, s5
	s_and_b32 s4, s9, 0xffe0
	s_sub_i32 s4, s8, s4
	s_bfe_i32 s5, s4, 0x80000
	s_bfe_u32 s5, s5, 0x3000c
	s_add_i32 s5, s4, s5
	s_bfe_i32 s6, s5, 0x80000
	s_and_b32 s5, s5, 0xf8
	s_sext_i32_i16 s6, s6
	s_sub_i32 s4, s4, s5
	s_sext_i32_i8 s4, s4
	s_lshl_b32 s5, s6, 3
	s_and_b32 s6, s5, 0xffffffc0
	s_lshl_b32 s4, s4, 5
	v_lshrrev_b32_e32 v1, 3, v212
	v_or_b32_e32 v26, s6, v1
	s_ashr_i32 s5, s4, 31
	s_lshl_b64 s[8:9], s[4:5], 2
	v_ashrrev_i32_e32 v27, 31, v26
	v_and_b32_e32 v36, 7, v0
	s_add_u32 s8, s10, s8
	v_lshlrev_b64 v[2:3], 10, v[26:27]
	v_or_b32_e32 v4, 8, v26
	v_or_b32_e32 v10, 16, v26
	v_or_b32_e32 v12, 24, v26
	v_or_b32_e32 v18, 32, v26
	v_or_b32_e32 v20, 40, v26
	v_or_b32_e32 v30, 48, v26
	v_or_b32_e32 v26, 56, v26
	s_addc_u32 s9, s7, s9
	v_lshlrev_b32_e32 v34, 4, v36
	v_mov_b32_e32 v35, 0
	v_ashrrev_i32_e32 v5, 31, v4
	v_ashrrev_i32_e32 v11, 31, v10
	v_ashrrev_i32_e32 v13, 31, v12
	v_ashrrev_i32_e32 v19, 31, v18
	v_ashrrev_i32_e32 v21, 31, v20
	v_ashrrev_i32_e32 v31, 31, v30
	v_ashrrev_i32_e32 v27, 31, v26
	v_lshl_add_u64 v[28:29], s[8:9], 0, v[34:35]
	v_lshlrev_b64 v[4:5], 10, v[4:5]
	v_lshlrev_b64 v[10:11], 10, v[10:11]
	v_lshlrev_b64 v[12:13], 10, v[12:13]
	v_lshlrev_b64 v[18:19], 10, v[18:19]
	v_lshlrev_b64 v[20:21], 10, v[20:21]
	v_lshlrev_b64 v[30:31], 10, v[30:31]
	v_lshlrev_b64 v[26:27], 10, v[26:27]
	v_lshl_add_u64 v[2:3], v[28:29], 0, v[2:3]
	v_lshl_add_u64 v[6:7], v[28:29], 0, v[4:5]
	v_lshl_add_u64 v[10:11], v[28:29], 0, v[10:11]
	v_lshl_add_u64 v[14:15], v[28:29], 0, v[12:13]
	v_lshl_add_u64 v[18:19], v[28:29], 0, v[18:19]
	v_lshl_add_u64 v[22:23], v[28:29], 0, v[20:21]
	v_lshl_add_u64 v[30:31], v[28:29], 0, v[30:31]
	v_lshl_add_u64 v[32:33], v[28:29], 0, v[26:27]
	global_load_dwordx4 v[2:5], v[2:3], off nt
	s_nop 0
	global_load_dwordx4 v[6:9], v[6:7], off nt
	s_nop 0
	global_load_dwordx4 v[10:13], v[10:11], off nt
	s_nop 0
	global_load_dwordx4 v[14:17], v[14:15], off nt
	s_nop 0
	global_load_dwordx4 v[18:21], v[18:19], off nt
	s_nop 0
	global_load_dwordx4 v[22:25], v[22:23], off nt
	s_nop 0
	global_load_dwordx4 v[26:29], v[30:31], off nt
	s_nop 0
	global_load_dwordx4 v[30:33], v[32:33], off nt
	v_readlane_b32 s58, v254, 20
	v_readlane_b32 s59, v254, 21
	v_readlane_b32 s60, v254, 22
	v_readlane_b32 s61, v254, 23
	v_readlane_b32 s62, v254, 24
	v_readlane_b32 s63, v254, 25
	v_readlane_b32 s64, v254, 26
	v_readlane_b32 s65, v254, 27
	v_readlane_b32 s66, v254, 28
	v_readlane_b32 s67, v254, 29
	v_readlane_b32 s68, v254, 30
	v_readlane_b32 s69, v254, 31
	v_readlane_b32 s70, v254, 32
	v_readlane_b32 s71, v254, 33
	v_mul_u32_u24_e32 v37, 0x84, v1
	v_add3_u32 v37, s1, v34, v37
	s_waitcnt vmcnt(7)
	ds_write2_b32 v37, v2, v3 offset1:1
	ds_write2_b32 v37, v4, v5 offset0:2 offset1:3
	v_add_u32_e32 v2, 0x420, v37
	s_waitcnt vmcnt(6)
	ds_write2_b32 v2, v6, v7 offset1:1
	v_add_u32_e32 v2, 0x428, v37
	ds_write2_b32 v2, v8, v9 offset1:1
	v_add_u32_e32 v2, 0x840, v37
	s_waitcnt vmcnt(5)
	ds_write2_b32 v2, v10, v11 offset1:1
	v_add_u32_e32 v2, 0x848, v37
	ds_write2_b32 v2, v12, v13 offset1:1
	v_add_u32_e32 v2, 0xc60, v37
	s_waitcnt vmcnt(4)
	ds_write2_b32 v2, v14, v15 offset1:1
	v_add_u32_e32 v2, 0xc68, v37
	ds_write2_b32 v2, v16, v17 offset1:1
	v_add_u32_e32 v2, 0x1080, v37
	s_waitcnt vmcnt(3)
	ds_write2_b32 v2, v18, v19 offset1:1
	v_add_u32_e32 v2, 0x1088, v37
	ds_write2_b32 v2, v20, v21 offset1:1
	v_add_u32_e32 v2, 0x14a0, v37
	s_waitcnt vmcnt(2)
	ds_write2_b32 v2, v22, v23 offset1:1
	v_add_u32_e32 v2, 0x14a8, v37
	ds_write2_b32 v2, v24, v25 offset1:1
	v_add_u32_e32 v2, 0x18c0, v37
	s_waitcnt vmcnt(1)
	ds_write2_b32 v2, v26, v27 offset1:1
	v_add_u32_e32 v2, 0x18c8, v37
	ds_write2_b32 v2, v28, v29 offset1:1
	v_add_u32_e32 v2, 0x1ce0, v37
	s_waitcnt vmcnt(0)
	ds_write2_b32 v2, v30, v31 offset1:1
	v_add_u32_e32 v2, 0x1ce8, v37
	ds_write2_b32 v2, v32, v33 offset1:1
	v_mul_u32_u24_e32 v4, 0x420, v36
	v_lshlrev_b32_e32 v5, 2, v1
	s_waitcnt lgkmcnt(0)
	s_ashr_i32 s7, s6, 31
	v_add3_u32 v28, s1, v4, v5
	s_lshl_b64 s[6:7], s[6:7], 1
	ds_read2_b32 v[6:7], v28 offset0:33 offset1:41
	ds_read2_b32 v[8:9], v28 offset1:8
	ds_read2_b32 v[10:11], v28 offset0:66 offset1:74
	ds_read2_b32 v[12:13], v28 offset0:99 offset1:107
	ds_read2_b32 v[14:15], v28 offset0:132 offset1:140
	ds_read2_b32 v[16:17], v28 offset0:165 offset1:173
	ds_read2_b32 v[18:19], v28 offset0:198 offset1:206
	ds_read2_b32 v[20:21], v28 offset0:231 offset1:239
	s_add_u32 s6, s11, s6
	s_addc_u32 s7, s12, s7
	v_or_b32_e32 v24, s4, v1
	v_lshl_add_u64 v[2:3], s[6:7], 0, v[34:35]
	s_mov_b64 s[6:7], 0x2000000
	v_ashrrev_i32_e32 v25, 31, v24
	v_lshl_add_u64 v[22:23], v[2:3], 0, s[6:7]
	v_lshlrev_b64 v[26:27], 9, v[24:25]
	s_waitcnt lgkmcnt(6)
	v_cvt_pk_bf16_f32 v2, v8, v6
	s_waitcnt lgkmcnt(4)
	v_cvt_pk_bf16_f32 v3, v10, v12
	s_waitcnt lgkmcnt(2)
	v_cvt_pk_bf16_f32 v4, v14, v16
	s_waitcnt lgkmcnt(0)
	v_cvt_pk_bf16_f32 v5, v18, v20
	v_lshl_add_u64 v[26:27], v[22:23], 0, v[26:27]
	v_or_b32_e32 v6, 8, v24
	global_store_dwordx4 v[26:27], v[2:5], off
	s_nop 1
	v_cvt_pk_bf16_f32 v2, v9, v7
	v_ashrrev_i32_e32 v7, 31, v6
	v_cvt_pk_bf16_f32 v3, v11, v13
	v_cvt_pk_bf16_f32 v4, v15, v17
	v_cvt_pk_bf16_f32 v5, v19, v21
	v_lshlrev_b64 v[6:7], 9, v[6:7]
	ds_read2_b32 v[8:9], v28 offset0:49 offset1:57
	ds_read2_b32 v[10:11], v28 offset0:16 offset1:24
	ds_read2_b32 v[12:13], v28 offset0:82 offset1:90
	ds_read2_b32 v[14:15], v28 offset0:115 offset1:123
	ds_read2_b32 v[16:17], v28 offset0:148 offset1:156
	ds_read2_b32 v[18:19], v28 offset0:181 offset1:189
	ds_read2_b32 v[20:21], v28 offset0:214 offset1:222
	ds_read2_b32 v[26:27], v28 offset0:247 offset1:255
	v_lshl_add_u64 v[6:7], v[22:23], 0, v[6:7]
	global_store_dwordx4 v[6:7], v[2:5], off
	v_or_b32_e32 v6, 16, v24
	v_ashrrev_i32_e32 v7, 31, v6
	v_lshlrev_b64 v[6:7], 9, v[6:7]
	s_waitcnt lgkmcnt(6)
	v_cvt_pk_bf16_f32 v2, v10, v8
	s_waitcnt lgkmcnt(4)
	v_cvt_pk_bf16_f32 v3, v12, v14
	s_waitcnt lgkmcnt(2)
	v_cvt_pk_bf16_f32 v4, v16, v18
	s_waitcnt lgkmcnt(0)
	v_cvt_pk_bf16_f32 v5, v20, v26
	v_lshl_add_u64 v[6:7], v[22:23], 0, v[6:7]
	global_store_dwordx4 v[6:7], v[2:5], off
	v_or_b32_e32 v6, 24, v24
	v_ashrrev_i32_e32 v7, 31, v6
	v_lshlrev_b64 v[6:7], 9, v[6:7]
	v_cvt_pk_bf16_f32 v2, v11, v9
	v_cvt_pk_bf16_f32 v3, v13, v15
	v_cvt_pk_bf16_f32 v4, v17, v19
	v_cvt_pk_bf16_f32 v5, v21, v27
	v_lshl_add_u64 v[6:7], v[22:23], 0, v[6:7]
	global_store_dwordx4 v[6:7], v[2:5], off
	s_waitcnt lgkmcnt(0)
	s_cmp_eq_u32 s98, 1
	s_cbranch_scc1 .Lp0_ret
	s_add_i32 s8, s16, 0xffffff40
	s_cmpk_gt_u32 s16, 0xcf
	s_cbranch_scc1 .LBB0_42

; #define LAS __attribute__((address_space(3)))
; #define SUB(i, ...) do { if (PROBE_PH == phk && PROBE_SUB == (i)) { __syncthreads(); tp0 = __builtin_amdgcn_s_memrealtime(); } __VA_ARGS__ if (PROBE_PH == phk && PROBE_SUB == (i)) { asm volatile("s_waitcnt vmcnt(0)" ::: "memory"); __syncthreads(); tp1 = __builtin_amdgcn_s_memrealtime(); } } while (0)
; __global__ void __launch_bounds__(NTHREADS, 2) mk_fwd(Args a) {
;     ...
;         SUB(0, if (bx < 192) gemv_item((LAS float*)lds, bx, a.in[1], a.in[3], a.in[4], a.in[5], (float*)(a.ws + WS_MOD));
;                else { const int b2 = bx - 192;
;                    transpose_dispatch((16 + b2) * 8 + wave, a.in[7], a.in[20], a.in[18], a.in[8], a.ws, scr, lane);
;                    if (b2 < 16) transpose_dispatch(b2 * 8 + wave, a.in[7], a.in[20], a.in[18], a.in[8], a.ws, scr, lane);
;                    for (int it = 80 + 3 * b2; it < 80 + 3 * b2 + 3; ++it) transpose_dispatch(it * 8 + wave, a.in[7], a.in[20], a.in[18], a.in[8], a.ws, scr, lane);
;                    if (b2 >= 16) transpose_dispatch((272 + b2 - 16) * 8 + wave, a.in[7], a.in[20], a.in[18], a.in[8], a.ws, scr, lane); } );
.LBB0_69:
	s_mov_b64 s[4:5], 0
	s_branch .LBB0_70
.Lp0_ret:
	s_sub_i32 s16, s16, 0xc0
	s_mov_b32 s98, 0
	s_mov_b64 s[4:5], -1
	s_waitcnt lgkmcnt(0)
	s_barrier
